# stack19 + seam elimination: XCC-local grid barrier replaced by a workgroup barrier where consecutive chunk phases share no data (w_out(c)->w_in(c+1), merge(c)->qkv(c+1))
# baseline (speedup 1.0000x reference)
.LBB0_9:
	v_readlane_b32 s0, v251, 15
	s_cmp_lg_u32 s60, s0
	s_mov_b64 s[0:1], -1
	s_cbranch_scc0 .LBB0_99
	v_readlane_b32 s0, v251, 15
	s_cmp_le_i32 s60, s0
	s_cbranch_scc1 .LBB0_98
	v_readlane_b32 s0, v249, 37
	s_nop 1
	v_mov_b32_e32 v0, s0
	ds_read_b32 v0, v0
	s_waitcnt lgkmcnt(0)
	v_readfirstlane_b32 s0, v0
	s_cmp_lg_u32 s0, 1
	s_cbranch_scc1 .LBB0_16
	s_ashr_i32 s61, s60, 31
	s_lshl_b64 s[0:1], s[60:61], 2
	s_getpc_b64 s[2:3]
	s_add_u32 s2, s2, _ZL6d_prog@rel32@lo+4
	s_addc_u32 s3, s3, _ZL6d_prog@rel32@hi+12
	s_add_u32 s0, s2, s0
	s_addc_u32 s1, s3, s1
	s_load_dword s7, s[0:1], 0x0
	s_waitcnt lgkmcnt(0)
	s_and_b32 s6, s7, 0xff
	s_bfe_u32 s8, s7, 0x80010
	s_cmp_eq_u32 s8, 0
	s_cbranch_scc1 .Lseam_keep
	s_cmp_eq_u32 s6, 9
	s_cbranch_scc1 .Lseam_skip
	s_cmp_eq_u32 s6, 13
	s_cbranch_scc1 .Lseam_skip
.Lseam_keep:
	s_cmp_lt_i32 s6, 9
	s_cbranch_scc1 .LBB0_17
	s_and_b32 s8, 0xffff, s6
	s_cmp_gt_i32 s8, 13
	s_cbranch_scc0 .LBB0_18
	s_cmp_gt_i32 s8, 16
	s_cbranch_scc0 .LBB0_19
	s_cmp_lg_u32 s8, 17
	s_mov_b64 s[2:3], -1
	s_cselect_b64 s[0:1], -1, 0
	s_cbranch_execz .LBB0_20
	s_branch .LBB0_21

.Lseam_skip:
	s_waitcnt vmcnt(0)
	s_barrier
	s_branch .LBB0_114
